# V^T epilogue own-token rs row loaded at K-loop start (spare VGPRs) so its latency is hidden
# speedup vs baseline: 1.0038x; 1.0015x over previous
.LBB0_212:
	s_ashr_i32 s41, s40, 31
	s_lshl_b64 s[14:15], s[40:41], 19
	s_add_u32 s42, s50, s14
	s_addc_u32 s43, s51, s15
	s_and_b64 s[14:15], s[28:29], exec
	s_cselect_b32 s14, s43, s5
	s_cselect_b32 s15, s42, s4
	s_ashr_i32 s31, s30, 31
	s_lshl_b64 s[44:45], s[30:31], 19
	s_add_u32 s44, s10, s44
	s_addc_u32 s45, s11, s45
	s_and_b64 s[48:49], s[28:29], exec
	s_cselect_b32 s31, s45, s19
	s_cselect_b32 s41, s44, s18
	s_add_u32 s4, s4, 0x40080
	s_addc_u32 s5, s5, 0
	s_add_u32 s59, s18, 0x100
	s_addc_u32 s60, s19, 0
	s_mov_b32 s61, -2
	v_and_b32_e32 v233, 15, v218
	v_and_b32_e32 v248, 8, v233
	v_and_b32_e32 v233, 7, v233
	v_lshl_add_u32 v233, v248, 4, v233
	v_lshl_or_b32 v248, s58, 8, v181
	v_add_lshl_u32 v233, v248, v233, 4
	global_load_dwordx4 v[248:251], v233, s[6:7]
	s_add_u32 s18, s4, 0xfffc0080
	s_addc_u32 s19, s5, -1
	s_add_i32 s62, 0, 0x10000
	s_cmp_eq_u32 s61, 12
	s_cselect_b32 s49, s14, s19
	s_cselect_b32 s48, s15, s18
	s_cselect_b32 s19, s31, s60
	s_cselect_b32 s18, s41, s59
	s_add_i32 s64, 0, 0x14000
	v_add_u32_e32 v144, s62, v180
	v_add_u32_e32 v166, s64, v180
	ds_read_b128 v[132:135], v144
	ds_read_b128 v[136:139], v144 offset:1024
	ds_read_b128 v[140:143], v144 offset:2048
	ds_read_b128 v[144:147], v144 offset:3072
	ds_read_b128 v[158:161], v166
	ds_read_b128 v[162:165], v166 offset:1024
	ds_read_b128 v[176:179], v166 offset:2048
	ds_read_b128 v[184:187], v166 offset:3072
	v_lshl_add_u64 v[166:167], s[4:5], 0, v[154:155]
	s_add_i32 m0, s47, 0xc000
	ds_read_b128 v[188:191], v182
	ds_read_b128 v[192:195], v182 offset:1024
	ds_read_b128 v[196:199], v182 offset:2048
	ds_read_b128 v[200:203], v182 offset:3072
	ds_read_b128 v[204:207], v182 offset:4096
	ds_read_b128 v[208:211], v182 offset:5120
	ds_read_b128 v[234:237], v182 offset:6144
	ds_read_b128 v[238:241], v182 offset:7168
	global_load_lds_dwordx4 v[166:167], off
	v_lshl_add_u64 v[166:167], s[4:5], 0, v[156:157]
	s_add_i32 m0, s47, 0xe000
	s_nop 0
	global_load_lds_dwordx4 v[166:167], off
	s_waitcnt vmcnt(8)
	s_waitcnt lgkmcnt(0)
	s_barrier
	s_setprio 1
	s_waitcnt lgkmcnt(0)
	v_mfma_f32_16x16x32_bf16 v[128:131], v[132:135], v[188:191], 0
	v_mfma_f32_16x16x32_bf16 v[124:127], v[140:143], v[188:191], 0
	v_mfma_f32_16x16x32_bf16 v[116:119], v[132:135], v[196:199], 0
	v_mfma_f32_16x16x32_bf16 v[108:111], v[140:143], v[196:199], 0
	v_mfma_f32_16x16x32_bf16 v[100:103], v[132:135], v[204:207], 0
	v_mfma_f32_16x16x32_bf16 v[92:95], v[140:143], v[204:207], 0
	v_mfma_f32_16x16x32_bf16 v[84:87], v[132:135], v[234:237], 0
	v_mfma_f32_16x16x32_bf16 v[76:79], v[140:143], v[234:237], 0
	v_mfma_f32_16x16x32_bf16 v[128:131], v[136:139], v[192:195], v[128:131]
	v_mfma_f32_16x16x32_bf16 v[124:127], v[144:147], v[192:195], v[124:127]
	v_mfma_f32_16x16x32_bf16 v[116:119], v[136:139], v[200:203], v[116:119]
	v_mfma_f32_16x16x32_bf16 v[108:111], v[144:147], v[200:203], v[108:111]
	v_mfma_f32_16x16x32_bf16 v[100:103], v[136:139], v[208:211], v[100:103]
	v_mfma_f32_16x16x32_bf16 v[92:95], v[144:147], v[208:211], v[92:95]
	v_mfma_f32_16x16x32_bf16 v[84:87], v[136:139], v[238:241], v[84:87]
	v_mfma_f32_16x16x32_bf16 v[76:79], v[144:147], v[238:241], v[76:79]
	s_setprio 0
	s_setprio 1
	v_mfma_f32_16x16x32_bf16 v[120:123], v[158:161], v[188:191], 0
	v_mfma_f32_16x16x32_bf16 v[112:115], v[176:179], v[188:191], 0
	v_mfma_f32_16x16x32_bf16 v[104:107], v[158:161], v[196:199], 0
	v_mfma_f32_16x16x32_bf16 v[96:99], v[176:179], v[196:199], 0
	v_mfma_f32_16x16x32_bf16 v[88:91], v[158:161], v[204:207], 0
	v_mfma_f32_16x16x32_bf16 v[80:83], v[176:179], v[204:207], 0
	v_mfma_f32_16x16x32_bf16 v[72:75], v[158:161], v[234:237], 0
	v_mfma_f32_16x16x32_bf16 v[68:71], v[176:179], v[234:237], 0
	v_mfma_f32_16x16x32_bf16 v[120:123], v[162:165], v[192:195], v[120:123]
	v_mfma_f32_16x16x32_bf16 v[112:115], v[184:187], v[192:195], v[112:115]
	v_mfma_f32_16x16x32_bf16 v[104:107], v[162:165], v[200:203], v[104:107]
	v_mfma_f32_16x16x32_bf16 v[96:99], v[184:187], v[200:203], v[96:99]
	v_mfma_f32_16x16x32_bf16 v[88:91], v[162:165], v[208:211], v[88:91]
	v_mfma_f32_16x16x32_bf16 v[80:83], v[184:187], v[208:211], v[80:83]
	v_mfma_f32_16x16x32_bf16 v[72:75], v[162:165], v[238:241], v[72:75]
	v_mfma_f32_16x16x32_bf16 v[68:71], v[184:187], v[238:241], v[68:71]
	s_setprio 0
	s_barrier
	s_add_i32 s62, s62, s34
	v_lshl_add_u64 v[166:167], s[18:19], 0, v[2:3]
	s_mov_b32 m0, s62
	ds_read_b128 v[188:191], v182 offset:16384
	ds_read_b128 v[192:195], v182 offset:17408
	ds_read_b128 v[196:199], v182 offset:18432
	ds_read_b128 v[200:203], v182 offset:19456
	ds_read_b128 v[204:207], v182 offset:20480
	ds_read_b128 v[208:211], v182 offset:21504
	ds_read_b128 v[234:237], v182 offset:22528
	ds_read_b128 v[238:241], v182 offset:23552
	global_load_lds_dwordx4 v[166:167], off
	s_add_i32 m0, s62, 0x2000
	s_add_u32 s62, s18, 0x40000
	v_lshl_add_u64 v[212:213], s[18:19], 0, v[152:153]
	s_addc_u32 s63, s19, 0
	s_add_i32 s64, s64, s34
	global_load_lds_dwordx4 v[212:213], off
	v_lshl_add_u64 v[242:243], s[62:63], 0, v[2:3]
	s_mov_b32 m0, s64
	v_lshl_add_u64 v[244:245], s[48:49], 0, v[150:151]
	global_load_lds_dwordx4 v[242:243], off
	v_lshl_add_u64 v[242:243], s[62:63], 0, v[152:153]
	s_add_i32 m0, s64, 0x2000
	s_nop 0
	global_load_lds_dwordx4 v[242:243], off
	v_lshl_add_u64 v[242:243], s[48:49], 0, v[148:149]
	s_mov_b32 m0, s47
	s_nop 0
	global_load_lds_dwordx4 v[242:243], off
	s_mov_b32 m0, s52
	s_nop 0
	global_load_lds_dwordx4 v[244:245], off
	s_waitcnt vmcnt(8)
	s_waitcnt lgkmcnt(0)
	s_barrier
	s_setprio 1
	s_waitcnt lgkmcnt(0)
	v_mfma_f32_16x16x32_bf16 v[64:67], v[132:135], v[188:191], 0
	v_mfma_f32_16x16x32_bf16 v[60:63], v[140:143], v[188:191], 0
	v_mfma_f32_16x16x32_bf16 v[52:55], v[132:135], v[196:199], 0
	v_mfma_f32_16x16x32_bf16 v[44:47], v[140:143], v[196:199], 0
	v_mfma_f32_16x16x32_bf16 v[36:39], v[132:135], v[204:207], 0
	v_mfma_f32_16x16x32_bf16 v[28:31], v[140:143], v[204:207], 0
	v_mfma_f32_16x16x32_bf16 v[20:23], v[132:135], v[234:237], 0
	v_mfma_f32_16x16x32_bf16 v[12:15], v[140:143], v[234:237], 0
	v_mfma_f32_16x16x32_bf16 v[64:67], v[136:139], v[192:195], v[64:67]
	v_mfma_f32_16x16x32_bf16 v[60:63], v[144:147], v[192:195], v[60:63]
	v_mfma_f32_16x16x32_bf16 v[52:55], v[136:139], v[200:203], v[52:55]
	v_mfma_f32_16x16x32_bf16 v[44:47], v[144:147], v[200:203], v[44:47]
	v_mfma_f32_16x16x32_bf16 v[36:39], v[136:139], v[208:211], v[36:39]
	v_mfma_f32_16x16x32_bf16 v[28:31], v[144:147], v[208:211], v[28:31]
	v_mfma_f32_16x16x32_bf16 v[20:23], v[136:139], v[238:241], v[20:23]
	v_mfma_f32_16x16x32_bf16 v[12:15], v[144:147], v[238:241], v[12:15]
	s_setprio 0
	s_setprio 1
	v_mfma_f32_16x16x32_bf16 v[56:59], v[158:161], v[188:191], 0
	v_mfma_f32_16x16x32_bf16 v[48:51], v[176:179], v[188:191], 0
	v_mfma_f32_16x16x32_bf16 v[40:43], v[158:161], v[196:199], 0
	v_mfma_f32_16x16x32_bf16 v[32:35], v[176:179], v[196:199], 0
	v_mfma_f32_16x16x32_bf16 v[24:27], v[158:161], v[204:207], 0
	v_mfma_f32_16x16x32_bf16 v[16:19], v[176:179], v[204:207], 0
	v_mfma_f32_16x16x32_bf16 v[8:11], v[158:161], v[234:237], 0
	v_mfma_f32_16x16x32_bf16 v[4:7], v[176:179], v[234:237], 0
	v_mfma_f32_16x16x32_bf16 v[56:59], v[162:165], v[192:195], v[56:59]
	v_mfma_f32_16x16x32_bf16 v[48:51], v[184:187], v[192:195], v[48:51]
	v_mfma_f32_16x16x32_bf16 v[40:43], v[162:165], v[200:203], v[40:43]
	v_mfma_f32_16x16x32_bf16 v[32:35], v[184:187], v[200:203], v[32:35]
	v_mfma_f32_16x16x32_bf16 v[24:27], v[162:165], v[208:211], v[24:27]
	v_mfma_f32_16x16x32_bf16 v[16:19], v[184:187], v[208:211], v[16:19]
	v_mfma_f32_16x16x32_bf16 v[8:11], v[162:165], v[238:241], v[8:11]
	v_mfma_f32_16x16x32_bf16 v[4:7], v[184:187], v[238:241], v[4:7]
	s_setprio 0
	s_barrier
	s_add_i32 s62, 0, 0x18000
	s_add_i32 s63, 0, 0x1c000
	v_add_u32_e32 v144, s62, v180
	v_add_u32_e32 v183, s63, v180
	ds_read_b128 v[132:135], v144
	ds_read_b128 v[136:139], v144 offset:1024
	ds_read_b128 v[140:143], v144 offset:2048
	ds_read_b128 v[144:147], v144 offset:3072
	ds_read_b128 v[158:161], v183
	ds_read_b128 v[162:165], v183 offset:1024
	ds_read_b128 v[176:179], v183 offset:2048
	ds_read_b128 v[184:187], v183 offset:3072
	s_add_u32 s48, s48, 0x40000
	s_addc_u32 s49, s49, 0
	s_mov_b32 m0, s53
	v_lshl_add_u64 v[246:247], s[48:49], 0, v[148:149]
	ds_read_b128 v[188:191], v182 offset:32768
	ds_read_b128 v[192:195], v182 offset:33792
	ds_read_b128 v[196:199], v182 offset:34816
	ds_read_b128 v[200:203], v182 offset:35840
	ds_read_b128 v[204:207], v182 offset:36864
	ds_read_b128 v[208:211], v182 offset:37888
	ds_read_b128 v[234:237], v182 offset:38912
	ds_read_b128 v[238:241], v182 offset:39936
	global_load_lds_dwordx4 v[246:247], off
	v_lshl_add_u64 v[246:247], s[48:49], 0, v[150:151]
	s_mov_b32 m0, s54
	s_nop 0
	global_load_lds_dwordx4 v[246:247], off
	s_waitcnt vmcnt(8)
	s_waitcnt lgkmcnt(0)
	s_barrier
	s_setprio 1
	s_waitcnt lgkmcnt(0)
	v_mfma_f32_16x16x32_bf16 v[128:131], v[132:135], v[188:191], v[128:131]
	v_mfma_f32_16x16x32_bf16 v[124:127], v[140:143], v[188:191], v[124:127]
	v_mfma_f32_16x16x32_bf16 v[116:119], v[132:135], v[196:199], v[116:119]
	v_mfma_f32_16x16x32_bf16 v[108:111], v[140:143], v[196:199], v[108:111]
	v_mfma_f32_16x16x32_bf16 v[100:103], v[132:135], v[204:207], v[100:103]
	v_mfma_f32_16x16x32_bf16 v[92:95], v[140:143], v[204:207], v[92:95]
	v_mfma_f32_16x16x32_bf16 v[84:87], v[132:135], v[234:237], v[84:87]
	v_mfma_f32_16x16x32_bf16 v[76:79], v[140:143], v[234:237], v[76:79]
	v_mfma_f32_16x16x32_bf16 v[128:131], v[136:139], v[192:195], v[128:131]
	v_mfma_f32_16x16x32_bf16 v[124:127], v[144:147], v[192:195], v[124:127]
	v_mfma_f32_16x16x32_bf16 v[116:119], v[136:139], v[200:203], v[116:119]
	v_mfma_f32_16x16x32_bf16 v[108:111], v[144:147], v[200:203], v[108:111]
	v_mfma_f32_16x16x32_bf16 v[100:103], v[136:139], v[208:211], v[100:103]
	v_mfma_f32_16x16x32_bf16 v[92:95], v[144:147], v[208:211], v[92:95]
	v_mfma_f32_16x16x32_bf16 v[84:87], v[136:139], v[238:241], v[84:87]
	v_mfma_f32_16x16x32_bf16 v[76:79], v[144:147], v[238:241], v[76:79]
	s_setprio 0
	s_setprio 1
	v_mfma_f32_16x16x32_bf16 v[120:123], v[158:161], v[188:191], v[120:123]
	v_mfma_f32_16x16x32_bf16 v[112:115], v[176:179], v[188:191], v[112:115]
	v_mfma_f32_16x16x32_bf16 v[104:107], v[158:161], v[196:199], v[104:107]
	v_mfma_f32_16x16x32_bf16 v[96:99], v[176:179], v[196:199], v[96:99]
	v_mfma_f32_16x16x32_bf16 v[88:91], v[158:161], v[204:207], v[88:91]
	v_mfma_f32_16x16x32_bf16 v[80:83], v[176:179], v[204:207], v[80:83]
	v_mfma_f32_16x16x32_bf16 v[72:75], v[158:161], v[234:237], v[72:75]
	v_mfma_f32_16x16x32_bf16 v[68:71], v[176:179], v[234:237], v[68:71]
	v_mfma_f32_16x16x32_bf16 v[120:123], v[162:165], v[192:195], v[120:123]
	v_mfma_f32_16x16x32_bf16 v[112:115], v[184:187], v[192:195], v[112:115]
	v_mfma_f32_16x16x32_bf16 v[104:107], v[162:165], v[200:203], v[104:107]
	v_mfma_f32_16x16x32_bf16 v[96:99], v[184:187], v[200:203], v[96:99]
	v_mfma_f32_16x16x32_bf16 v[88:91], v[162:165], v[208:211], v[88:91]
	v_mfma_f32_16x16x32_bf16 v[80:83], v[184:187], v[208:211], v[80:83]
	v_mfma_f32_16x16x32_bf16 v[72:75], v[162:165], v[238:241], v[72:75]
	v_mfma_f32_16x16x32_bf16 v[68:71], v[184:187], v[238:241], v[68:71]
	s_setprio 0
	s_barrier
	s_add_i32 s48, s62, s34
	v_lshl_add_u64 v[166:167], v[166:167], 0, s[16:17]
	s_mov_b32 m0, s48
	ds_read_b128 v[188:191], v182 offset:49152
	ds_read_b128 v[192:195], v182 offset:50176
	ds_read_b128 v[196:199], v182 offset:51200
	ds_read_b128 v[200:203], v182 offset:52224
	ds_read_b128 v[204:207], v182 offset:53248
	ds_read_b128 v[208:211], v182 offset:54272
	ds_read_b128 v[234:237], v182 offset:55296
	ds_read_b128 v[238:241], v182 offset:56320
	global_load_lds_dwordx4 v[166:167], off
	s_add_i32 m0, s48, 0x2000
	s_add_u32 s18, s18, 0x40080
	v_lshl_add_u64 v[166:167], v[212:213], 0, s[16:17]
	s_addc_u32 s19, s19, 0
	s_add_i32 s48, s63, s34
	global_load_lds_dwordx4 v[166:167], off
	v_lshl_add_u64 v[166:167], s[18:19], 0, v[2:3]
	s_mov_b32 m0, s48
	s_nop 0
	global_load_lds_dwordx4 v[166:167], off
	v_lshl_add_u64 v[166:167], s[18:19], 0, v[152:153]
	s_add_i32 m0, s48, 0x2000
	s_nop 0
	global_load_lds_dwordx4 v[166:167], off
	v_lshl_add_u64 v[166:167], v[242:243], 0, s[16:17]
	s_mov_b32 m0, s55
	s_nop 0
	global_load_lds_dwordx4 v[166:167], off
	v_lshl_add_u64 v[166:167], v[244:245], 0, s[16:17]
	s_mov_b32 m0, s56
	s_nop 0
	global_load_lds_dwordx4 v[166:167], off
	s_waitcnt vmcnt(8)
	s_waitcnt lgkmcnt(0)
	s_barrier
	s_setprio 1
	s_waitcnt lgkmcnt(0)
	v_mfma_f32_16x16x32_bf16 v[64:67], v[132:135], v[188:191], v[64:67]
	v_mfma_f32_16x16x32_bf16 v[60:63], v[140:143], v[188:191], v[60:63]
	v_mfma_f32_16x16x32_bf16 v[52:55], v[132:135], v[196:199], v[52:55]
	v_mfma_f32_16x16x32_bf16 v[44:47], v[140:143], v[196:199], v[44:47]
	v_mfma_f32_16x16x32_bf16 v[36:39], v[132:135], v[204:207], v[36:39]
	v_mfma_f32_16x16x32_bf16 v[28:31], v[140:143], v[204:207], v[28:31]
	v_mfma_f32_16x16x32_bf16 v[20:23], v[132:135], v[234:237], v[20:23]
	v_mfma_f32_16x16x32_bf16 v[12:15], v[140:143], v[234:237], v[12:15]
	v_mfma_f32_16x16x32_bf16 v[64:67], v[136:139], v[192:195], v[64:67]
	v_mfma_f32_16x16x32_bf16 v[60:63], v[144:147], v[192:195], v[60:63]
	v_mfma_f32_16x16x32_bf16 v[52:55], v[136:139], v[200:203], v[52:55]
	v_mfma_f32_16x16x32_bf16 v[44:47], v[144:147], v[200:203], v[44:47]
	v_mfma_f32_16x16x32_bf16 v[36:39], v[136:139], v[208:211], v[36:39]
	v_mfma_f32_16x16x32_bf16 v[28:31], v[144:147], v[208:211], v[28:31]
	v_mfma_f32_16x16x32_bf16 v[20:23], v[136:139], v[238:241], v[20:23]
	v_mfma_f32_16x16x32_bf16 v[12:15], v[144:147], v[238:241], v[12:15]
	s_setprio 0
	s_setprio 1
	v_mfma_f32_16x16x32_bf16 v[56:59], v[158:161], v[188:191], v[56:59]
	v_mfma_f32_16x16x32_bf16 v[48:51], v[176:179], v[188:191], v[48:51]
	v_mfma_f32_16x16x32_bf16 v[40:43], v[158:161], v[196:199], v[40:43]
	v_mfma_f32_16x16x32_bf16 v[32:35], v[176:179], v[196:199], v[32:35]
	v_mfma_f32_16x16x32_bf16 v[24:27], v[158:161], v[204:207], v[24:27]
	v_mfma_f32_16x16x32_bf16 v[16:19], v[176:179], v[204:207], v[16:19]
	v_mfma_f32_16x16x32_bf16 v[8:11], v[158:161], v[234:237], v[8:11]
	v_mfma_f32_16x16x32_bf16 v[4:7], v[176:179], v[234:237], v[4:7]
	v_mfma_f32_16x16x32_bf16 v[56:59], v[162:165], v[192:195], v[56:59]
	v_mfma_f32_16x16x32_bf16 v[48:51], v[184:187], v[192:195], v[48:51]
	v_mfma_f32_16x16x32_bf16 v[40:43], v[162:165], v[200:203], v[40:43]
	v_mfma_f32_16x16x32_bf16 v[32:35], v[184:187], v[200:203], v[32:35]
	v_mfma_f32_16x16x32_bf16 v[24:27], v[162:165], v[208:211], v[24:27]
	v_mfma_f32_16x16x32_bf16 v[16:19], v[184:187], v[208:211], v[16:19]
	v_mfma_f32_16x16x32_bf16 v[8:11], v[162:165], v[238:241], v[8:11]
	v_mfma_f32_16x16x32_bf16 v[4:7], v[184:187], v[238:241], v[4:7]
	s_setprio 0
	s_barrier
	s_add_i32 s61, s61, 2
	s_add_u32 s4, s4, 0x100
	s_addc_u32 s5, s5, 0
	s_add_u32 s59, s59, 0x100
	s_addc_u32 s60, s60, 0
	s_cmp_gt_u32 s61, 13

.LBB0_216:
	v_lshl_or_b32 v162, s58, 8, v181
	v_ashrrev_i32_e32 v163, 31, v162
	s_mov_b32 s14, 0xf800000
	s_waitcnt vmcnt(0)
	v_mov_b64_e32 v[186:187], v[248:249]
	v_mov_b64_e32 v[188:189], v[250:251]
	v_mov_b32_e32 v190, v187
	v_mov_b32_e32 v191, v188
	v_mov_b32_e32 v187, v189
	v_pk_add_f32 v[186:187], v[190:191], v[186:187]
	s_nop 1
	v_add_f32_e32 v186, v186, v187
	v_fmamk_f32 v186, v186, 0x3a800000, v215
	v_cmp_gt_f32_e32 vcc, s14, v186
	v_mul_f32_e32 v187, 0x4f800000, v186
	s_nop 1
	v_cndmask_b32_e32 v186, v186, v187, vcc
	v_sqrt_f32_e32 v187, v186
	s_nop 1
	v_add_u32_e32 v188, -1, v187
	v_fma_f32 v189, -v188, v187, v186
	v_cmp_ge_f32_e64 s[4:5], 0, v189
	v_add_u32_e32 v189, 1, v187
	s_nop 1
	v_cndmask_b32_e64 v188, v187, v188, s[4:5]
	v_fma_f32 v187, -v189, v187, v186
	v_cmp_lt_f32_e64 s[4:5], 0, v187
	s_nop 1
	v_cndmask_b32_e64 v187, v188, v189, s[4:5]
	v_mul_f32_e32 v188, 0x37800000, v187
	v_cndmask_b32_e32 v187, v187, v188, vcc
	v_cmp_class_f32_e32 vcc, v186, v216
	s_nop 1
	v_cndmask_b32_e32 v186, v187, v186, vcc
	v_div_scale_f32 v187, s[4:5], v186, v186, 1.0
	v_rcp_f32_e32 v188, v187
	s_nop 1
	v_fma_f32 v189, -v187, v188, 1.0
	v_fmac_f32_e32 v188, v189, v188
	v_div_scale_f32 v189, vcc, 1.0, v186, 1.0
	v_mul_f32_e32 v190, v189, v188
	v_fma_f32 v191, -v187, v190, v189
	v_fmac_f32_e32 v190, v191, v188
	v_fma_f32 v187, -v187, v190, v189
	v_div_fmas_f32 v187, v187, v188, v190
	v_div_fixup_f32 v190, v187, v186, 1.0
	v_mov_b32_e32 v233, v190
	s_nop 1
	s_waitcnt vmcnt(8)
	s_nop 1
	v_mov_b32_dpp v158, v233 row_newbcast:0 row_mask:0xf bank_mask:0xf
	s_nop 1
	v_mov_b32_dpp v159, v233 row_newbcast:1 row_mask:0xf bank_mask:0xf
	v_pk_mul_f32 v[128:129], v[128:129], v[158:159]
	v_pk_mul_f32 v[116:117], v[116:117], v[158:159]
	v_pk_mul_f32 v[100:101], v[100:101], v[158:159]
	v_pk_mul_f32 v[84:85], v[84:85], v[158:159]
	v_pk_mul_f32 v[64:65], v[64:65], v[158:159]
	v_pk_mul_f32 v[52:53], v[52:53], v[158:159]
	v_pk_mul_f32 v[36:37], v[36:37], v[158:159]
	v_pk_mul_f32 v[20:21], v[20:21], v[158:159]
	s_nop 1
	v_mov_b32_dpp v160, v233 row_newbcast:2 row_mask:0xf bank_mask:0xf
	s_nop 1
	v_mov_b32_dpp v161, v233 row_newbcast:3 row_mask:0xf bank_mask:0xf
	v_pk_mul_f32 v[130:131], v[130:131], v[160:161]
	v_pk_mul_f32 v[66:67], v[66:67], v[160:161]
	s_waitcnt vmcnt(4)
	s_nop 1
	v_mov_b32_dpp v164, v233 row_newbcast:4 row_mask:0xf bank_mask:0xf
	s_nop 1
	v_mov_b32_dpp v165, v233 row_newbcast:5 row_mask:0xf bank_mask:0xf
	s_nop 1
	v_mov_b32_dpp v166, v233 row_newbcast:6 row_mask:0xf bank_mask:0xf
	s_nop 1
	v_mov_b32_dpp v167, v233 row_newbcast:7 row_mask:0xf bank_mask:0xf
	s_waitcnt vmcnt(4)
	s_nop 1
	v_mov_b32_dpp v176, v233 row_newbcast:8 row_mask:0xf bank_mask:0xf
	s_nop 1
	v_mov_b32_dpp v177, v233 row_newbcast:9 row_mask:0xf bank_mask:0xf
	v_pk_mul_f32 v[120:121], v[120:121], v[176:177]
	v_pk_mul_f32 v[104:105], v[104:105], v[176:177]
	v_pk_mul_f32 v[88:89], v[88:89], v[176:177]
	v_pk_mul_f32 v[72:73], v[72:73], v[176:177]
	v_pk_mul_f32 v[56:57], v[56:57], v[176:177]
	v_pk_mul_f32 v[40:41], v[40:41], v[176:177]
	v_pk_mul_f32 v[24:25], v[24:25], v[176:177]
	v_pk_mul_f32 v[8:9], v[8:9], v[176:177]
	s_nop 1
	v_mov_b32_dpp v178, v233 row_newbcast:10 row_mask:0xf bank_mask:0xf
	s_nop 1
	v_mov_b32_dpp v179, v233 row_newbcast:11 row_mask:0xf bank_mask:0xf
	v_pk_mul_f32 v[122:123], v[122:123], v[178:179]
	v_pk_mul_f32 v[106:107], v[106:107], v[178:179]
	v_pk_mul_f32 v[90:91], v[90:91], v[178:179]
	v_pk_mul_f32 v[74:75], v[74:75], v[178:179]
	v_pk_mul_f32 v[58:59], v[58:59], v[178:179]
	v_pk_mul_f32 v[42:43], v[42:43], v[178:179]
	v_pk_mul_f32 v[26:27], v[26:27], v[178:179]
	v_pk_mul_f32 v[10:11], v[10:11], v[178:179]
	s_waitcnt vmcnt(0)
	s_nop 1
	v_mov_b32_dpp v144, v233 row_newbcast:12 row_mask:0xf bank_mask:0xf
	s_nop 1
	v_mov_b32_dpp v145, v233 row_newbcast:13 row_mask:0xf bank_mask:0xf
	s_nop 1
	v_mov_b32_dpp v136, v233 row_newbcast:14 row_mask:0xf bank_mask:0xf
	v_pk_mul_f32 v[140:141], v[126:127], v[166:167]
	v_pk_mul_f32 v[126:127], v[124:125], v[164:165]
	v_cvt_pk_bf16_f32 v124, v128, v129
	v_cvt_pk_bf16_f32 v125, v130, v131
	v_cvt_pk_bf16_f32 v126, v126, v127
	v_cvt_pk_bf16_f32 v127, v140, v141
	s_nop 1
	s_mov_b64 s[4:5], 0x400000
	v_lshl_add_u32 v134, s46, 8, v1
	v_ashrrev_i32_e32 v135, 31, v134
	v_mov_b32_dpp v137, v233 row_newbcast:15 row_mask:0xf bank_mask:0xf
	v_lshlrev_b64 v[132:133], 15, v[134:135]
	v_lshl_add_u64 v[132:133], s[22:23], 0, v[132:133]
	v_lshlrev_b64 v[138:139], 1, v[162:163]
	v_lshl_add_u64 v[132:133], v[132:133], 0, v[138:139]
	global_store_dwordx4 v[132:133], v[124:127], off
	s_nop 1
	v_pk_mul_f32 v[124:125], v[114:115], v[136:137]
	v_pk_mul_f32 v[114:115], v[112:113], v[144:145]
	v_cvt_pk_bf16_f32 v112, v120, v121
	v_cvt_pk_bf16_f32 v113, v122, v123
	s_nop 1
	v_cvt_pk_bf16_f32 v114, v114, v115
	v_cvt_pk_bf16_f32 v115, v124, v125
	global_store_dwordx4 v[132:133], v[112:115], off offset:256
	s_nop 1
	v_or_b32_e32 v112, 16, v134
	v_ashrrev_i32_e32 v113, 31, v112
	v_lshlrev_b64 v[112:113], 15, v[112:113]
	v_lshl_add_u64 v[112:113], s[22:23], 0, v[112:113]
	v_lshl_add_u64 v[112:113], v[112:113], 0, v[138:139]
	v_pk_mul_f32 v[114:115], v[118:119], v[160:161]
	v_pk_mul_f32 v[118:119], v[110:111], v[166:167]
	v_pk_mul_f32 v[110:111], v[108:109], v[164:165]
	v_cvt_pk_bf16_f32 v108, v116, v117
	v_cvt_pk_bf16_f32 v109, v114, v115
	s_nop 1
	v_cvt_pk_bf16_f32 v110, v110, v111
	v_cvt_pk_bf16_f32 v111, v118, v119
	global_store_dwordx4 v[112:113], v[108:111], off
	s_nop 1
	v_pk_mul_f32 v[108:109], v[98:99], v[136:137]
	v_pk_mul_f32 v[98:99], v[96:97], v[144:145]
	v_cvt_pk_bf16_f32 v96, v104, v105
	v_cvt_pk_bf16_f32 v97, v106, v107
	s_nop 1
	v_cvt_pk_bf16_f32 v98, v98, v99
	v_cvt_pk_bf16_f32 v99, v108, v109
	global_store_dwordx4 v[112:113], v[96:99], off offset:256
	s_nop 1
	v_or_b32_e32 v96, 32, v134
	v_ashrrev_i32_e32 v97, 31, v96
	v_lshlrev_b64 v[96:97], 15, v[96:97]
	v_lshl_add_u64 v[96:97], s[22:23], 0, v[96:97]
	v_lshl_add_u64 v[96:97], v[96:97], 0, v[138:139]
	v_pk_mul_f32 v[98:99], v[102:103], v[160:161]
	v_pk_mul_f32 v[102:103], v[94:95], v[166:167]
	v_pk_mul_f32 v[94:95], v[92:93], v[164:165]
	v_cvt_pk_bf16_f32 v92, v100, v101
	v_cvt_pk_bf16_f32 v93, v98, v99
	s_nop 1
	v_cvt_pk_bf16_f32 v94, v94, v95
	v_cvt_pk_bf16_f32 v95, v102, v103
	global_store_dwordx4 v[96:97], v[92:95], off
	s_nop 1
	v_pk_mul_f32 v[92:93], v[82:83], v[136:137]
	v_pk_mul_f32 v[82:83], v[80:81], v[144:145]
	v_cvt_pk_bf16_f32 v80, v88, v89
	v_cvt_pk_bf16_f32 v81, v90, v91
	s_nop 1
	v_cvt_pk_bf16_f32 v82, v82, v83
	v_cvt_pk_bf16_f32 v83, v92, v93
	global_store_dwordx4 v[96:97], v[80:83], off offset:256
	s_nop 1
	v_or_b32_e32 v80, 48, v134
	v_ashrrev_i32_e32 v81, 31, v80
	v_lshlrev_b64 v[80:81], 15, v[80:81]
	v_lshl_add_u64 v[80:81], s[22:23], 0, v[80:81]
	v_lshl_add_u64 v[80:81], v[80:81], 0, v[138:139]
	v_pk_mul_f32 v[82:83], v[86:87], v[160:161]
	v_pk_mul_f32 v[86:87], v[78:79], v[166:167]
	v_pk_mul_f32 v[78:79], v[76:77], v[164:165]
	v_cvt_pk_bf16_f32 v76, v84, v85
	v_cvt_pk_bf16_f32 v77, v82, v83
	s_nop 1
	v_cvt_pk_bf16_f32 v78, v78, v79
	v_cvt_pk_bf16_f32 v79, v86, v87
	global_store_dwordx4 v[80:81], v[76:79], off
	s_nop 1
	v_pk_mul_f32 v[76:77], v[70:71], v[136:137]
	v_pk_mul_f32 v[70:71], v[68:69], v[144:145]
	v_cvt_pk_bf16_f32 v68, v72, v73
	v_cvt_pk_bf16_f32 v69, v74, v75
	s_nop 1
	v_cvt_pk_bf16_f32 v70, v70, v71
	v_cvt_pk_bf16_f32 v71, v76, v77
	global_store_dwordx4 v[80:81], v[68:71], off offset:256
	s_nop 1
	v_lshl_add_u64 v[68:69], v[132:133], 0, s[4:5]
	s_mov_b32 s4, 0x400000
	v_pk_mul_f32 v[70:71], v[62:63], v[166:167]
	v_pk_mul_f32 v[62:63], v[60:61], v[164:165]
	v_cvt_pk_bf16_f32 v60, v64, v65
	v_add_co_u32_e32 v64, vcc, s4, v132
	v_cvt_pk_bf16_f32 v61, v66, v67
	v_cvt_pk_bf16_f32 v62, v62, v63
	v_cvt_pk_bf16_f32 v63, v70, v71
	s_mov_b64 s[4:5], 0x480000
	s_nop 1
	v_addc_co_u32_e32 v65, vcc, 0, v133, vcc
	global_store_dwordx4 v[64:65], v[60:63], off
	s_nop 1
	v_pk_mul_f32 v[60:61], v[50:51], v[136:137]
	v_pk_mul_f32 v[50:51], v[48:49], v[144:145]
	v_cvt_pk_bf16_f32 v48, v56, v57
	v_cvt_pk_bf16_f32 v49, v58, v59
	s_nop 1
	v_cvt_pk_bf16_f32 v50, v50, v51
	v_cvt_pk_bf16_f32 v51, v60, v61
	global_store_dwordx4 v[68:69], v[48:51], off offset:256
	s_nop 1
	v_lshl_add_u64 v[48:49], v[132:133], 0, s[4:5]
	v_pk_mul_f32 v[50:51], v[54:55], v[160:161]
	s_mov_b32 s4, 0x480000
	v_pk_mul_f32 v[54:55], v[46:47], v[166:167]
	v_pk_mul_f32 v[46:47], v[44:45], v[164:165]
	v_cvt_pk_bf16_f32 v44, v52, v53
	v_cvt_pk_bf16_f32 v45, v50, v51
	v_add_co_u32_e32 v50, vcc, s4, v132
	v_cvt_pk_bf16_f32 v46, v46, v47
	v_cvt_pk_bf16_f32 v47, v54, v55
	s_mov_b64 s[4:5], 0x500000
	s_nop 1
	v_addc_co_u32_e32 v51, vcc, 0, v133, vcc
	global_store_dwordx4 v[50:51], v[44:47], off
	s_nop 1
	v_pk_mul_f32 v[44:45], v[34:35], v[136:137]
	v_pk_mul_f32 v[34:35], v[32:33], v[144:145]
	v_cvt_pk_bf16_f32 v32, v40, v41
	v_cvt_pk_bf16_f32 v33, v42, v43
	s_nop 1
	v_cvt_pk_bf16_f32 v34, v34, v35
	v_cvt_pk_bf16_f32 v35, v44, v45
	global_store_dwordx4 v[48:49], v[32:35], off offset:256
	s_nop 1
	v_lshl_add_u64 v[32:33], v[132:133], 0, s[4:5]
	v_pk_mul_f32 v[34:35], v[38:39], v[160:161]
	s_mov_b32 s4, 0x500000
	v_pk_mul_f32 v[38:39], v[30:31], v[166:167]
	v_pk_mul_f32 v[30:31], v[28:29], v[164:165]
	v_cvt_pk_bf16_f32 v28, v36, v37
	v_cvt_pk_bf16_f32 v29, v34, v35
	v_add_co_u32_e32 v34, vcc, s4, v132
	v_cvt_pk_bf16_f32 v30, v30, v31
	v_cvt_pk_bf16_f32 v31, v38, v39
	s_mov_b64 s[4:5], 0x580000
	s_nop 1
	v_addc_co_u32_e32 v35, vcc, 0, v133, vcc
	global_store_dwordx4 v[34:35], v[28:31], off
	s_nop 1
	v_pk_mul_f32 v[28:29], v[18:19], v[136:137]
	v_pk_mul_f32 v[18:19], v[16:17], v[144:145]
	v_cvt_pk_bf16_f32 v16, v24, v25
	v_cvt_pk_bf16_f32 v17, v26, v27
	s_nop 1
	v_cvt_pk_bf16_f32 v18, v18, v19
	v_cvt_pk_bf16_f32 v19, v28, v29
	global_store_dwordx4 v[32:33], v[16:19], off offset:256
	s_nop 1
	v_lshl_add_u64 v[16:17], v[132:133], 0, s[4:5]
	v_pk_mul_f32 v[18:19], v[22:23], v[160:161]
	s_mov_b32 s4, 0x580000
	v_pk_mul_f32 v[22:23], v[14:15], v[166:167]
	v_pk_mul_f32 v[14:15], v[12:13], v[164:165]
	v_cvt_pk_bf16_f32 v12, v20, v21
	v_cvt_pk_bf16_f32 v13, v18, v19
	v_add_co_u32_e32 v18, vcc, s4, v132
	v_cvt_pk_bf16_f32 v14, v14, v15
	v_cvt_pk_bf16_f32 v15, v22, v23
	s_mov_b64 s[4:5], -1
	s_nop 1
	v_addc_co_u32_e32 v19, vcc, 0, v133, vcc
	global_store_dwordx4 v[18:19], v[12:15], off
	s_andn2_b64 vcc, exec, s[28:29]
	s_nop 1
	v_pk_mul_f32 v[12:13], v[6:7], v[136:137]
	v_pk_mul_f32 v[6:7], v[4:5], v[144:145]
	v_cvt_pk_bf16_f32 v4, v8, v9
	v_cvt_pk_bf16_f32 v5, v10, v11
	s_nop 1
	v_cvt_pk_bf16_f32 v6, v6, v7
	v_cvt_pk_bf16_f32 v7, v12, v13
	global_store_dwordx4 v[16:17], v[4:7], off offset:256
	s_cbranch_vccnz .LBB0_205
	s_andn2_b64 vcc, exec, s[24:25]
	s_cbranch_vccnz .LBB0_204
	s_barrier
	s_branch .LBB0_204
